# MLA loops: V fragments 3 and 4 prefetched with 1 and 2 into the consumed K-fragment registers v232-247 (no LDS round trip between PV MFMAs)
# baseline (speedup 1.0000x reference)
.LBB0_710:
	s_mov_b32 s35, s4
	s_mov_b32 s4, s52
	global_load_dwordx4 v[204:207], v192, s[98:99] offset:128
	global_load_dwordx4 v[208:211], v188, s[98:99]
	global_load_dwordx2 v[218:219], v214, s[98:99] offset:-2048
	ds_read_b128 v[118:121], v199 offset:17424
	ds_read_b128 v[114:117], v199 offset:17408
	ds_read_b128 v[130:133], v199 offset:22016
	ds_read_b128 v[134:137], v199 offset:22032
	ds_read_b128 v[242:245], v199 offset:17488
	ds_read_b128 v[238:241], v199 offset:17472
	s_waitcnt lgkmcnt(4)
	v_add_f32_e32 v160, v86, v82
	v_mfma_scale_f32_32x32x64_f8f6f4 v[114:129], v[114:119], v[168:173], v[50:65], v120, v194 op_sel_hi:[0,0,0] cbsz:2 blgp:2
	v_cvt_pk_fp8_f32 v154, v82, v83
	v_cvt_pk_fp8_f32 v155, v98, v99
	v_cvt_pk_fp8_f32 v154, v84, v85 op_sel:[0,0,1]
	v_cvt_pk_fp8_f32 v155, v100, v101 op_sel:[0,0,1]
	v_add_f32_e32 v82, v87, v83
	v_add_f32_e32 v83, v88, v84
	v_permlane32_swap_b32_e32 v154, v155
	ds_read_b128 v[246:249], v199 offset:22080
	ds_read_b128 v[250:253], v199 offset:22096
	v_add_f32_e32 v84, v89, v85
	s_waitcnt lgkmcnt(3)
	v_mfma_scale_f32_32x32x64_f8f6f4 v[130:145], v[130:135], v[168:173], v[50:65], v136, v194 op_sel_hi:[0,0,0] cbsz:2 blgp:2
	v_add_f32_e32 v85, v90, v160
	v_add_f32_e32 v82, v91, v82
	v_add_f32_e32 v83, v92, v83
	v_add_f32_e32 v84, v93, v84
	v_add_f32_e32 v159, v94, v85
	v_add_f32_e32 v160, v95, v82
	v_add_f32_e32 v161, v96, v83
	v_add_f32_e32 v186, v97, v84
	ds_read_b128 v[230:233], v222 offset:5120
	ds_read_b128 v[234:237], v222 offset:5136
	s_waitcnt lgkmcnt(4)
	v_mfma_scale_f32_32x32x64_f8f6f4 v[114:129], v[238:243], v[162:167], v[114:129], v244, v190 op_sel_hi:[0,0,0] cbsz:2 blgp:2
	v_cvt_pk_fp8_f32 v156, v86, v87
	v_cvt_pk_fp8_f32 v157, v102, v103
	v_cvt_pk_fp8_f32 v156, v88, v89 op_sel:[0,0,1]
	v_cvt_pk_fp8_f32 v157, v104, v105 op_sel:[0,0,1]
	v_add_f32_e32 v98, v98, v159
	v_add_f32_e32 v99, v99, v160
	v_permlane32_swap_b32_e32 v156, v157
	v_add_f32_e32 v100, v100, v161
	v_add_f32_e32 v101, v101, v186
	v_add_f32_e32 v98, v102, v98
	ds_read_b128 v[82:85], v222 offset:7680
	ds_read_b128 v[86:89], v222 offset:7696
	s_waitcnt lgkmcnt(4)
	v_mfma_scale_f32_32x32x64_f8f6f4 v[130:145], v[246:251], v[162:167], v[130:145], v252, v190 op_sel_hi:[0,0,0] cbsz:2 blgp:2
	v_cvt_pk_fp8_f32 v158, v90, v91
	v_cvt_pk_fp8_f32 v159, v106, v107
	v_cvt_pk_fp8_f32 v158, v92, v93 op_sel:[0,0,1]
	v_cvt_pk_fp8_f32 v159, v108, v109 op_sel:[0,0,1]
	v_add_f32_e32 v90, v103, v99
	v_add_f32_e32 v91, v104, v100
	v_permlane32_swap_b32_e32 v158, v159
	v_add_f32_e32 v92, v105, v101
	s_waitcnt lgkmcnt(2)
	v_mfma_scale_f32_32x32x64_f8f6f4 v[114:129], v[230:237], v[146:153], v[114:129], v220, v1 op_sel_hi:[0,0,0]
	v_add_f32_e32 v93, v106, v98
	v_add_f32_e32 v90, v107, v90
	v_add_f32_e32 v91, v108, v91
	v_add_f32_e32 v92, v109, v92
	v_add_f32_e32 v93, v110, v93
	v_add_f32_e32 v90, v111, v90
	v_add_f32_e32 v91, v112, v91
	v_add_f32_e32 v92, v113, v92
	v_cvt_pk_fp8_f32 v160, v94, v95
	v_cvt_pk_fp8_f32 v161, v110, v111
	v_cvt_pk_fp8_f32 v160, v96, v97 op_sel:[0,0,1]
	v_cvt_pk_fp8_f32 v161, v112, v113 op_sel:[0,0,1]
	s_waitcnt lgkmcnt(0)
	v_mfma_scale_f32_32x32x64_f8f6f4 v[130:145], v[82:89], v[146:153], v[130:145], v220, v1 op_sel_hi:[0,0,0]
	v_add_f32_e32 v82, v93, v90
	v_add_f32_e32 v83, v91, v92
	v_permlane32_swap_b32_e32 v160, v161
	v_add_f32_e32 v229, v82, v83
	v_mov_b32_e32 v230, v229
	v_add_u32_e32 v82, s5, v224
	s_waitcnt vmcnt(0)
	ds_write_b128 v82, v[204:207]
	ds_write_b128 v225, v[208:211] offset:49152
	ds_write_b64 v226, v[218:219]
	v_add_u32_e32 v98, s4, v191
	ds_read_b128 v[90:93], v98
	ds_read_b128 v[94:97], v98 offset:16
	v_max3_f32 v82, v114, s88, v115
	v_max3_f32 v82, v82, v116, v117
	v_max3_f32 v82, v82, v118, v119
	v_permlane32_swap_b32_e32 v229, v230
	v_max3_f32 v99, v82, v120, v121
	ds_read_b128 v[82:85], v98 offset:2560
	ds_read_b128 v[86:89], v98 offset:2576
	ds_read_b128 v[232:235], v98 offset:5120
	ds_read_b128 v[236:239], v98 offset:5136
	ds_read_b128 v[240:243], v98 offset:7680
	ds_read_b128 v[244:247], v98 offset:7696
	v_max3_f32 v99, v99, v122, v123
	v_max3_f32 v99, v99, v124, v125
	v_max3_f32 v99, v99, v126, v127
	v_max3_f32 v99, v99, v128, v129
	s_waitcnt lgkmcnt(6)
	v_mfma_scale_f32_32x32x64_f8f6f4 v[66:81], v[90:97], v[154:161], v[66:81], v220, v220 op_sel_hi:[0,0,0]
	v_max3_f32 v99, v99, v130, v131
	v_max3_f32 v99, v99, v132, v133
	v_max3_f32 v99, v99, v134, v135
	v_max3_f32 v99, v99, v136, v137
	v_max3_f32 v99, v99, v138, v139
	v_max3_f32 v99, v99, v140, v141
	v_max3_f32 v99, v99, v142, v143
	v_max3_f32 v99, v99, v144, v145
	v_mov_b32_e32 v100, v99
	v_mov_b32_e32 v186, 1.0
	s_nop 0
	v_permlane32_swap_b32_e32 v99, v100
	v_max_f32_e32 v99, v99, v100
	v_cmp_ge_f32_e32 vcc, s89, v99
	s_cmp_eq_u64 vcc, exec
	s_cbranch_scc1 .LBB0_712
	v_add_f32_e32 v99, -4.0, v99
	v_max_f32_e32 v99, 0, v99
	v_exp_f32_e64 v186, -v99
	v_sub_f32_e32 v129, v129, v99
	v_sub_f32_e32 v128, v128, v99
	v_sub_f32_e32 v127, v127, v99
	v_sub_f32_e32 v126, v126, v99
	v_sub_f32_e32 v125, v125, v99
	v_sub_f32_e32 v124, v124, v99
	v_sub_f32_e32 v123, v123, v99
	v_sub_f32_e32 v122, v122, v99
	v_sub_f32_e32 v121, v121, v99
	v_sub_f32_e32 v120, v120, v99
	v_sub_f32_e32 v119, v119, v99
	v_sub_f32_e32 v118, v118, v99
	v_sub_f32_e32 v117, v117, v99
	v_sub_f32_e32 v116, v116, v99
	v_sub_f32_e32 v115, v115, v99
	v_sub_f32_e32 v114, v114, v99
	v_sub_f32_e32 v145, v145, v99
	v_sub_f32_e32 v144, v144, v99
	v_sub_f32_e32 v143, v143, v99
	v_sub_f32_e32 v142, v142, v99
	v_sub_f32_e32 v141, v141, v99
	v_sub_f32_e32 v140, v140, v99
	v_sub_f32_e32 v139, v139, v99
	v_sub_f32_e32 v138, v138, v99
	v_sub_f32_e32 v137, v137, v99
	v_sub_f32_e32 v136, v136, v99
	v_sub_f32_e32 v135, v135, v99
	v_sub_f32_e32 v134, v134, v99
	v_sub_f32_e32 v133, v133, v99
	v_sub_f32_e32 v132, v132, v99
	v_sub_f32_e32 v131, v131, v99
	v_sub_f32_e32 v130, v130, v99
	v_sub_f32_e32 v65, v65, v99
	v_sub_f32_e32 v64, v64, v99
	v_sub_f32_e32 v63, v63, v99
	v_sub_f32_e32 v62, v62, v99
	v_sub_f32_e32 v61, v61, v99
	v_sub_f32_e32 v60, v60, v99
	v_sub_f32_e32 v59, v59, v99
	v_sub_f32_e32 v58, v58, v99
	v_sub_f32_e32 v57, v57, v99
	v_sub_f32_e32 v56, v56, v99
	v_sub_f32_e32 v55, v55, v99
	v_sub_f32_e32 v54, v54, v99
	v_sub_f32_e32 v53, v53, v99
	v_sub_f32_e32 v52, v52, v99
	v_sub_f32_e32 v51, v51, v99
	v_sub_f32_e32 v50, v50, v99
.LBB0_712:
	s_waitcnt lgkmcnt(4)
	v_mfma_scale_f32_32x32x64_f8f6f4 v[34:49], v[82:89], v[154:161], v[34:49], v220, v220 op_sel_hi:[0,0,0]
	v_exp_f32_e32 v114, v114
	v_exp_f32_e32 v115, v115
	v_exp_f32_e32 v116, v116
	v_exp_f32_e32 v117, v117
	v_exp_f32_e32 v118, v118
	v_exp_f32_e32 v119, v119
	v_exp_f32_e32 v120, v120
	v_exp_f32_e32 v121, v121
	v_exp_f32_e32 v122, v122
	v_exp_f32_e32 v123, v123
	v_exp_f32_e32 v124, v124
	v_exp_f32_e32 v125, v125
	v_exp_f32_e32 v126, v126
	v_exp_f32_e32 v127, v127
	v_exp_f32_e32 v128, v128
	v_exp_f32_e32 v129, v129
	s_waitcnt lgkmcnt(2)
	v_mfma_scale_f32_32x32x64_f8f6f4 v[18:33], v[232:239], v[154:161], v[18:33], v220, v220 op_sel_hi:[0,0,0]
	v_exp_f32_e32 v130, v130
	v_exp_f32_e32 v131, v131
	v_exp_f32_e32 v132, v132
	v_exp_f32_e32 v133, v133
	v_exp_f32_e32 v134, v134
	v_exp_f32_e32 v135, v135
	v_exp_f32_e32 v136, v136
	v_exp_f32_e32 v137, v137
	v_exp_f32_e32 v138, v138
	v_exp_f32_e32 v139, v139
	v_exp_f32_e32 v140, v140
	v_exp_f32_e32 v141, v141
	v_exp_f32_e32 v142, v142
	v_exp_f32_e32 v143, v143
	v_exp_f32_e32 v144, v144
	v_exp_f32_e32 v145, v145
	s_waitcnt lgkmcnt(0)
	v_mfma_scale_f32_32x32x64_f8f6f4 v[2:17], v[240:247], v[154:161], v[2:17], v220, v220 op_sel_hi:[0,0,0]
	v_cmp_gt_f32_e32 vcc, 1.0, v186
	s_cbranch_vccz .LBB0_714
	v_pk_mul_f32 v[80:81], v[80:81], v[186:187] op_sel_hi:[1,0]
	v_pk_mul_f32 v[78:79], v[78:79], v[186:187] op_sel_hi:[1,0]
	v_pk_mul_f32 v[76:77], v[76:77], v[186:187] op_sel_hi:[1,0]
	v_pk_mul_f32 v[74:75], v[74:75], v[186:187] op_sel_hi:[1,0]
	v_pk_mul_f32 v[72:73], v[72:73], v[186:187] op_sel_hi:[1,0]
	v_pk_mul_f32 v[70:71], v[70:71], v[186:187] op_sel_hi:[1,0]
	v_pk_mul_f32 v[68:69], v[68:69], v[186:187] op_sel_hi:[1,0]
	v_pk_mul_f32 v[66:67], v[66:67], v[186:187] op_sel_hi:[1,0]
	v_pk_mul_f32 v[48:49], v[48:49], v[186:187] op_sel_hi:[1,0]
	v_pk_mul_f32 v[46:47], v[46:47], v[186:187] op_sel_hi:[1,0]
	v_pk_mul_f32 v[44:45], v[44:45], v[186:187] op_sel_hi:[1,0]
	v_pk_mul_f32 v[42:43], v[42:43], v[186:187] op_sel_hi:[1,0]
	v_pk_mul_f32 v[40:41], v[40:41], v[186:187] op_sel_hi:[1,0]
	v_pk_mul_f32 v[38:39], v[38:39], v[186:187] op_sel_hi:[1,0]
	v_pk_mul_f32 v[36:37], v[36:37], v[186:187] op_sel_hi:[1,0]
	v_pk_mul_f32 v[34:35], v[34:35], v[186:187] op_sel_hi:[1,0]
	v_pk_mul_f32 v[32:33], v[186:187], v[32:33] op_sel_hi:[0,1]
	v_pk_mul_f32 v[30:31], v[186:187], v[30:31] op_sel_hi:[0,1]
	v_pk_mul_f32 v[28:29], v[186:187], v[28:29] op_sel_hi:[0,1]
	v_pk_mul_f32 v[26:27], v[186:187], v[26:27] op_sel_hi:[0,1]
	v_pk_mul_f32 v[24:25], v[186:187], v[24:25] op_sel_hi:[0,1]
	v_pk_mul_f32 v[22:23], v[186:187], v[22:23] op_sel_hi:[0,1]
	v_pk_mul_f32 v[20:21], v[186:187], v[20:21] op_sel_hi:[0,1]
	v_pk_mul_f32 v[18:19], v[186:187], v[18:19] op_sel_hi:[0,1]
	v_pk_mul_f32 v[16:17], v[186:187], v[16:17] op_sel_hi:[0,1]
	v_pk_mul_f32 v[14:15], v[186:187], v[14:15] op_sel_hi:[0,1]
	v_pk_mul_f32 v[12:13], v[186:187], v[12:13] op_sel_hi:[0,1]
	v_pk_mul_f32 v[10:11], v[186:187], v[10:11] op_sel_hi:[0,1]
	v_pk_mul_f32 v[8:9], v[186:187], v[8:9] op_sel_hi:[0,1]
	v_pk_mul_f32 v[6:7], v[186:187], v[6:7] op_sel_hi:[0,1]
	v_pk_mul_f32 v[4:5], v[186:187], v[4:5] op_sel_hi:[0,1]
	v_pk_mul_f32 v[2:3], v[186:187], v[2:3] op_sel_hi:[0,1]
.LBB0_714:
	s_barrier
	global_load_dwordx4 v[204:207], v192, s[98:99] offset:192
	global_load_dwordx4 v[208:211], v189, s[98:99]
	global_load_dwordx2 v[196:197], v214, s[98:99] offset:2048
	ds_read_b128 v[86:89], v223 offset:49168
	ds_read_b128 v[82:85], v223 offset:49152
	ds_read_b128 v[98:101], v223 offset:53760
	ds_read_b128 v[102:105], v223 offset:53776
	ds_read_b128 v[156:159], v223 offset:49232
	ds_read_b128 v[240:243], v223 offset:49216
	s_waitcnt lgkmcnt(4)
	v_add_f32_e32 v160, v118, v114
	v_mfma_scale_f32_32x32x64_f8f6f4 v[82:97], v[82:87], v[174:179], v[50:65], v88, v198 op_sel_hi:[0,0,0] cbsz:2 blgp:2
	v_cvt_pk_fp8_f32 v154, v114, v115
	v_cvt_pk_fp8_f32 v155, v130, v131
	v_cvt_pk_fp8_f32 v154, v116, v117 op_sel:[0,0,1]
	v_cvt_pk_fp8_f32 v155, v132, v133 op_sel:[0,0,1]
	v_add_f32_e32 v114, v119, v115
	v_add_f32_e32 v115, v120, v116
	v_permlane32_swap_b32_e32 v154, v155
	ds_read_b128 v[246:249], v223 offset:53824
	ds_read_b128 v[250:253], v223 offset:53840
	v_add_f32_e32 v116, v121, v117
	s_waitcnt lgkmcnt(3)
	v_mfma_scale_f32_32x32x64_f8f6f4 v[98:113], v[98:103], v[174:179], v[50:65], v104, v198 op_sel_hi:[0,0,0] cbsz:2 blgp:2
	v_add_f32_e32 v117, v122, v160
	v_add_f32_e32 v114, v123, v114
	v_mov_b32_e32 v244, v156
	v_mov_b32_e32 v245, v157
	v_add_f32_e32 v115, v124, v115
	v_add_f32_e32 v116, v125, v116
	v_add_f32_e32 v159, v126, v117
	v_add_f32_e32 v160, v127, v114
	v_add_f32_e32 v161, v128, v115
	v_add_f32_e32 v200, v129, v116
	ds_read_b128 v[232:235], v222
	ds_read_b128 v[236:239], v222 offset:16
	s_waitcnt lgkmcnt(4)
	v_mfma_scale_f32_32x32x64_f8f6f4 v[82:97], v[240:245], v[180:185], v[82:97], v158, v202 op_sel_hi:[0,0,0] cbsz:2 blgp:2
	v_cvt_pk_fp8_f32 v156, v118, v119
	v_cvt_pk_fp8_f32 v157, v134, v135
	v_cvt_pk_fp8_f32 v156, v120, v121 op_sel:[0,0,1]
	v_cvt_pk_fp8_f32 v157, v136, v137 op_sel:[0,0,1]
	v_add_f32_e32 v130, v130, v159
	v_add_f32_e32 v131, v131, v160
	v_permlane32_swap_b32_e32 v156, v157
	s_waitcnt lgkmcnt(2)
	v_add_f32_e32 v132, v132, v161
	v_add_f32_e32 v133, v133, v200
	v_add_f32_e32 v130, v134, v130
	ds_read_b128 v[114:117], v222 offset:2560
	ds_read_b128 v[118:121], v222 offset:2576
	v_mfma_scale_f32_32x32x64_f8f6f4 v[98:113], v[246:251], v[180:185], v[98:113], v252, v202 op_sel_hi:[0,0,0] cbsz:2 blgp:2
	v_cvt_pk_fp8_f32 v158, v122, v123
	v_cvt_pk_fp8_f32 v159, v138, v139
	v_cvt_pk_fp8_f32 v158, v124, v125 op_sel:[0,0,1]
	v_cvt_pk_fp8_f32 v159, v140, v141 op_sel:[0,0,1]
	v_add_f32_e32 v122, v135, v131
	v_add_f32_e32 v123, v136, v132
	v_permlane32_swap_b32_e32 v158, v159
	v_add_f32_e32 v124, v137, v133
	s_waitcnt lgkmcnt(2)
	v_mfma_scale_f32_32x32x64_f8f6f4 v[82:97], v[232:239], v[146:153], v[82:97], v220, v1 op_sel_hi:[0,0,0]
	v_add_f32_e32 v125, v138, v130
	v_add_f32_e32 v122, v139, v122
	v_add_f32_e32 v123, v140, v123
	v_add_f32_e32 v124, v141, v124
	v_add_f32_e32 v125, v142, v125
	v_add_f32_e32 v122, v143, v122
	v_add_f32_e32 v123, v144, v123
	v_add_f32_e32 v124, v145, v124
	v_cvt_pk_fp8_f32 v160, v126, v127
	v_cvt_pk_fp8_f32 v161, v142, v143
	v_cvt_pk_fp8_f32 v160, v128, v129 op_sel:[0,0,1]
	v_cvt_pk_fp8_f32 v161, v144, v145 op_sel:[0,0,1]
	s_waitcnt lgkmcnt(0)
	v_mfma_scale_f32_32x32x64_f8f6f4 v[98:113], v[114:121], v[146:153], v[98:113], v220, v1 op_sel_hi:[0,0,0]
	v_add_f32_e32 v114, v125, v122
	v_add_f32_e32 v115, v123, v124
	v_permlane32_swap_b32_e32 v160, v161
	v_add_f32_e32 v130, v114, v115
	v_mov_b32_e32 v131, v130
	v_add_u32_e32 v114, s4, v224
	s_waitcnt vmcnt(0)
	ds_write_b128 v114, v[204:207]
	ds_write_b128 v203, v[208:211]
	ds_write_b64 v227, v[196:197]
	v_add_u32_e32 v132, s35, v191
	ds_read_b128 v[122:125], v132
	ds_read_b128 v[126:129], v132 offset:16
	v_max3_f32 v114, v82, s88, v83
	v_max3_f32 v114, v114, v84, v85
	v_max3_f32 v114, v114, v86, v87
	v_permlane32_swap_b32_e32 v130, v131
	v_max3_f32 v133, v114, v88, v89
	ds_read_b128 v[114:117], v132 offset:2560
	ds_read_b128 v[118:121], v132 offset:2576
	ds_read_b128 v[232:235], v132 offset:5120
	ds_read_b128 v[236:239], v132 offset:5136
	ds_read_b128 v[240:243], v132 offset:7680
	ds_read_b128 v[244:247], v132 offset:7696
	v_max3_f32 v133, v133, v90, v91
	v_max3_f32 v133, v133, v92, v93
	v_max3_f32 v133, v133, v94, v95
	v_max3_f32 v133, v133, v96, v97
	s_waitcnt lgkmcnt(6)
	v_mfma_scale_f32_32x32x64_f8f6f4 v[66:81], v[122:129], v[154:161], v[66:81], v220, v220 op_sel_hi:[0,0,0]
	v_max3_f32 v133, v133, v98, v99
	v_max3_f32 v133, v133, v100, v101
	v_max3_f32 v133, v133, v102, v103
	v_max3_f32 v133, v133, v104, v105
	v_max3_f32 v133, v133, v106, v107
	v_max3_f32 v133, v133, v108, v109
	v_max3_f32 v133, v133, v110, v111
	v_max3_f32 v133, v133, v112, v113
	v_mov_b32_e32 v134, v133
	v_mov_b32_e32 v138, 1.0
	s_nop 0
	v_permlane32_swap_b32_e32 v133, v134
	v_max_f32_e32 v133, v133, v134
	v_cmp_ge_f32_e32 vcc, s89, v133
	s_cmp_eq_u64 vcc, exec
	s_cbranch_scc1 .LBB0_716
	v_add_f32_e32 v133, -4.0, v133
	v_max_f32_e32 v133, 0, v133
	v_exp_f32_e64 v138, -v133
	v_sub_f32_e32 v97, v97, v133
	v_sub_f32_e32 v96, v96, v133
	v_sub_f32_e32 v95, v95, v133
	v_sub_f32_e32 v94, v94, v133
	v_sub_f32_e32 v93, v93, v133
	v_sub_f32_e32 v92, v92, v133
	v_sub_f32_e32 v91, v91, v133
	v_sub_f32_e32 v90, v90, v133
	v_sub_f32_e32 v89, v89, v133
	v_sub_f32_e32 v88, v88, v133
	v_sub_f32_e32 v87, v87, v133
	v_sub_f32_e32 v86, v86, v133
	v_sub_f32_e32 v85, v85, v133
	v_sub_f32_e32 v84, v84, v133
	v_sub_f32_e32 v83, v83, v133
	v_sub_f32_e32 v82, v82, v133
	v_sub_f32_e32 v113, v113, v133
	v_sub_f32_e32 v112, v112, v133
	v_sub_f32_e32 v111, v111, v133
	v_sub_f32_e32 v110, v110, v133
	v_sub_f32_e32 v109, v109, v133
	v_sub_f32_e32 v108, v108, v133
	v_sub_f32_e32 v107, v107, v133
	v_sub_f32_e32 v106, v106, v133
	v_sub_f32_e32 v105, v105, v133
	v_sub_f32_e32 v104, v104, v133
	v_sub_f32_e32 v103, v103, v133
	v_sub_f32_e32 v102, v102, v133
	v_sub_f32_e32 v101, v101, v133
	v_sub_f32_e32 v100, v100, v133
	v_sub_f32_e32 v99, v99, v133
	v_sub_f32_e32 v98, v98, v133
	v_sub_f32_e32 v65, v65, v133
	v_sub_f32_e32 v64, v64, v133
	v_sub_f32_e32 v63, v63, v133
	v_sub_f32_e32 v62, v62, v133
	v_sub_f32_e32 v61, v61, v133
	v_sub_f32_e32 v60, v60, v133
	v_sub_f32_e32 v59, v59, v133
	v_sub_f32_e32 v58, v58, v133
	v_sub_f32_e32 v57, v57, v133
	v_sub_f32_e32 v56, v56, v133
	v_sub_f32_e32 v55, v55, v133
	v_sub_f32_e32 v54, v54, v133
	v_sub_f32_e32 v53, v53, v133
	v_sub_f32_e32 v52, v52, v133
	v_sub_f32_e32 v51, v51, v133
	v_sub_f32_e32 v50, v50, v133
.LBB0_716:
	s_waitcnt lgkmcnt(4)
	v_mfma_scale_f32_32x32x64_f8f6f4 v[34:49], v[114:121], v[154:161], v[34:49], v220, v220 op_sel_hi:[0,0,0]
	v_exp_f32_e32 v82, v82
	v_exp_f32_e32 v83, v83
	v_exp_f32_e32 v84, v84
	v_exp_f32_e32 v85, v85
	v_exp_f32_e32 v86, v86
	v_exp_f32_e32 v87, v87
	v_exp_f32_e32 v88, v88
	v_exp_f32_e32 v89, v89
	v_exp_f32_e32 v90, v90
	v_exp_f32_e32 v91, v91
	v_exp_f32_e32 v92, v92
	v_exp_f32_e32 v93, v93
	v_exp_f32_e32 v94, v94
	v_exp_f32_e32 v95, v95
	v_exp_f32_e32 v96, v96
	v_exp_f32_e32 v97, v97
	s_waitcnt lgkmcnt(2)
	v_mfma_scale_f32_32x32x64_f8f6f4 v[18:33], v[232:239], v[154:161], v[18:33], v220, v220 op_sel_hi:[0,0,0]
	v_exp_f32_e32 v98, v98
	v_exp_f32_e32 v99, v99
	v_exp_f32_e32 v100, v100
	v_exp_f32_e32 v101, v101
	v_exp_f32_e32 v102, v102
	v_exp_f32_e32 v103, v103
	v_exp_f32_e32 v104, v104
	v_exp_f32_e32 v105, v105
	v_exp_f32_e32 v106, v106
	v_exp_f32_e32 v107, v107
	v_exp_f32_e32 v108, v108
	v_exp_f32_e32 v109, v109
	v_exp_f32_e32 v110, v110
	v_exp_f32_e32 v111, v111
	v_exp_f32_e32 v112, v112
	v_exp_f32_e32 v113, v113
	s_waitcnt lgkmcnt(0)
	v_mfma_scale_f32_32x32x64_f8f6f4 v[2:17], v[240:247], v[154:161], v[2:17], v220, v220 op_sel_hi:[0,0,0]
	v_cmp_gt_f32_e32 vcc, 1.0, v138
	s_cbranch_vccz .LBB0_718
	v_pk_mul_f32 v[80:81], v[80:81], v[138:139] op_sel_hi:[1,0]
	v_pk_mul_f32 v[78:79], v[78:79], v[138:139] op_sel_hi:[1,0]
	v_pk_mul_f32 v[76:77], v[76:77], v[138:139] op_sel_hi:[1,0]
	v_pk_mul_f32 v[74:75], v[74:75], v[138:139] op_sel_hi:[1,0]
	v_pk_mul_f32 v[72:73], v[72:73], v[138:139] op_sel_hi:[1,0]
	v_pk_mul_f32 v[70:71], v[70:71], v[138:139] op_sel_hi:[1,0]
	v_pk_mul_f32 v[68:69], v[68:69], v[138:139] op_sel_hi:[1,0]
	v_pk_mul_f32 v[66:67], v[66:67], v[138:139] op_sel_hi:[1,0]
	v_pk_mul_f32 v[48:49], v[48:49], v[138:139] op_sel_hi:[1,0]
	v_pk_mul_f32 v[46:47], v[46:47], v[138:139] op_sel_hi:[1,0]
	v_pk_mul_f32 v[44:45], v[44:45], v[138:139] op_sel_hi:[1,0]
	v_pk_mul_f32 v[42:43], v[42:43], v[138:139] op_sel_hi:[1,0]
	v_pk_mul_f32 v[40:41], v[40:41], v[138:139] op_sel_hi:[1,0]
	v_pk_mul_f32 v[38:39], v[38:39], v[138:139] op_sel_hi:[1,0]
	v_pk_mul_f32 v[36:37], v[36:37], v[138:139] op_sel_hi:[1,0]
	v_pk_mul_f32 v[34:35], v[34:35], v[138:139] op_sel_hi:[1,0]
	v_pk_mul_f32 v[32:33], v[138:139], v[32:33] op_sel_hi:[0,1]
	v_pk_mul_f32 v[30:31], v[138:139], v[30:31] op_sel_hi:[0,1]
	v_pk_mul_f32 v[28:29], v[138:139], v[28:29] op_sel_hi:[0,1]
	v_pk_mul_f32 v[26:27], v[138:139], v[26:27] op_sel_hi:[0,1]
	v_pk_mul_f32 v[24:25], v[138:139], v[24:25] op_sel_hi:[0,1]
	v_pk_mul_f32 v[22:23], v[138:139], v[22:23] op_sel_hi:[0,1]
	v_pk_mul_f32 v[20:21], v[138:139], v[20:21] op_sel_hi:[0,1]
	v_pk_mul_f32 v[18:19], v[138:139], v[18:19] op_sel_hi:[0,1]
	v_pk_mul_f32 v[16:17], v[138:139], v[16:17] op_sel_hi:[0,1]
	v_pk_mul_f32 v[14:15], v[138:139], v[14:15] op_sel_hi:[0,1]
	v_pk_mul_f32 v[12:13], v[138:139], v[12:13] op_sel_hi:[0,1]
	v_pk_mul_f32 v[10:11], v[138:139], v[10:11] op_sel_hi:[0,1]
	v_pk_mul_f32 v[8:9], v[138:139], v[8:9] op_sel_hi:[0,1]
	v_pk_mul_f32 v[6:7], v[138:139], v[6:7] op_sel_hi:[0,1]
	v_pk_mul_f32 v[4:5], v[138:139], v[4:5] op_sel_hi:[0,1]
	v_pk_mul_f32 v[2:3], v[138:139], v[2:3] op_sel_hi:[0,1]

.LBB0_1733:
	s_mov_b32 s10, s4
	s_mov_b32 s4, s8
	global_load_dwordx4 v[204:207], v192, s[98:99] offset:128
	global_load_dwordx4 v[208:211], v188, s[98:99]
	global_load_dwordx2 v[218:219], v214, s[98:99] offset:-2048
	ds_read_b128 v[118:121], v199 offset:17424
	ds_read_b128 v[114:117], v199 offset:17408
	ds_read_b128 v[130:133], v199 offset:22016
	ds_read_b128 v[134:137], v199 offset:22032
	ds_read_b128 v[242:245], v199 offset:17488
	ds_read_b128 v[238:241], v199 offset:17472
	s_waitcnt lgkmcnt(4)
	v_add_f32_e32 v160, v86, v82
	v_mfma_scale_f32_32x32x64_f8f6f4 v[114:129], v[114:119], v[168:173], v[50:65], v120, v194 op_sel_hi:[0,0,0] cbsz:2 blgp:2
	v_cvt_pk_fp8_f32 v154, v82, v83
	v_cvt_pk_fp8_f32 v155, v98, v99
	v_cvt_pk_fp8_f32 v154, v84, v85 op_sel:[0,0,1]
	v_cvt_pk_fp8_f32 v155, v100, v101 op_sel:[0,0,1]
	v_add_f32_e32 v82, v87, v83
	v_add_f32_e32 v83, v88, v84
	v_permlane32_swap_b32_e32 v154, v155
	ds_read_b128 v[246:249], v199 offset:22080
	ds_read_b128 v[250:253], v199 offset:22096
	v_add_f32_e32 v84, v89, v85
	s_waitcnt lgkmcnt(3)
	v_mfma_scale_f32_32x32x64_f8f6f4 v[130:145], v[130:135], v[168:173], v[50:65], v136, v194 op_sel_hi:[0,0,0] cbsz:2 blgp:2
	v_add_f32_e32 v85, v90, v160
	v_add_f32_e32 v82, v91, v82
	v_add_f32_e32 v83, v92, v83
	v_add_f32_e32 v84, v93, v84
	v_add_f32_e32 v159, v94, v85
	v_add_f32_e32 v160, v95, v82
	v_add_f32_e32 v161, v96, v83
	v_add_f32_e32 v186, v97, v84
	ds_read_b128 v[230:233], v222 offset:5120
	ds_read_b128 v[234:237], v222 offset:5136
	s_waitcnt lgkmcnt(4)
	v_mfma_scale_f32_32x32x64_f8f6f4 v[114:129], v[238:243], v[162:167], v[114:129], v244, v190 op_sel_hi:[0,0,0] cbsz:2 blgp:2
	v_cvt_pk_fp8_f32 v156, v86, v87
	v_cvt_pk_fp8_f32 v157, v102, v103
	v_cvt_pk_fp8_f32 v156, v88, v89 op_sel:[0,0,1]
	v_cvt_pk_fp8_f32 v157, v104, v105 op_sel:[0,0,1]
	v_add_f32_e32 v98, v98, v159
	v_add_f32_e32 v99, v99, v160
	v_permlane32_swap_b32_e32 v156, v157
	v_add_f32_e32 v100, v100, v161
	v_add_f32_e32 v101, v101, v186
	v_add_f32_e32 v98, v102, v98
	ds_read_b128 v[82:85], v222 offset:7680
	ds_read_b128 v[86:89], v222 offset:7696
	s_waitcnt lgkmcnt(4)
	v_mfma_scale_f32_32x32x64_f8f6f4 v[130:145], v[246:251], v[162:167], v[130:145], v252, v190 op_sel_hi:[0,0,0] cbsz:2 blgp:2
	v_cvt_pk_fp8_f32 v158, v90, v91
	v_cvt_pk_fp8_f32 v159, v106, v107
	v_cvt_pk_fp8_f32 v158, v92, v93 op_sel:[0,0,1]
	v_cvt_pk_fp8_f32 v159, v108, v109 op_sel:[0,0,1]
	v_add_f32_e32 v90, v103, v99
	v_add_f32_e32 v91, v104, v100
	v_permlane32_swap_b32_e32 v158, v159
	v_add_f32_e32 v92, v105, v101
	s_waitcnt lgkmcnt(2)
	v_mfma_scale_f32_32x32x64_f8f6f4 v[114:129], v[230:237], v[146:153], v[114:129], v220, v1 op_sel_hi:[0,0,0]
	v_add_f32_e32 v93, v106, v98
	v_add_f32_e32 v90, v107, v90
	v_add_f32_e32 v91, v108, v91
	v_add_f32_e32 v92, v109, v92
	v_add_f32_e32 v93, v110, v93
	v_add_f32_e32 v90, v111, v90
	v_add_f32_e32 v91, v112, v91
	v_add_f32_e32 v92, v113, v92
	v_cvt_pk_fp8_f32 v160, v94, v95
	v_cvt_pk_fp8_f32 v161, v110, v111
	v_cvt_pk_fp8_f32 v160, v96, v97 op_sel:[0,0,1]
	v_cvt_pk_fp8_f32 v161, v112, v113 op_sel:[0,0,1]
	s_waitcnt lgkmcnt(0)
	v_mfma_scale_f32_32x32x64_f8f6f4 v[130:145], v[82:89], v[146:153], v[130:145], v220, v1 op_sel_hi:[0,0,0]
	v_add_f32_e32 v82, v93, v90
	v_add_f32_e32 v83, v91, v92
	v_permlane32_swap_b32_e32 v160, v161
	v_add_f32_e32 v229, v82, v83
	v_mov_b32_e32 v230, v229
	v_add_u32_e32 v82, s5, v224
	s_waitcnt vmcnt(0)
	ds_write_b128 v82, v[204:207]
	ds_write_b128 v225, v[208:211] offset:49152
	ds_write_b64 v226, v[218:219]
	v_add_u32_e32 v98, s4, v191
	ds_read_b128 v[90:93], v98
	ds_read_b128 v[94:97], v98 offset:16
	v_max3_f32 v82, v114, s87, v115
	v_max3_f32 v82, v82, v116, v117
	v_max3_f32 v82, v82, v118, v119
	v_permlane32_swap_b32_e32 v229, v230
	v_max3_f32 v99, v82, v120, v121
	ds_read_b128 v[82:85], v98 offset:2560
	ds_read_b128 v[86:89], v98 offset:2576
	ds_read_b128 v[232:235], v98 offset:5120
	ds_read_b128 v[236:239], v98 offset:5136
	ds_read_b128 v[240:243], v98 offset:7680
	ds_read_b128 v[244:247], v98 offset:7696
	v_max3_f32 v99, v99, v122, v123
	v_max3_f32 v99, v99, v124, v125
	v_max3_f32 v99, v99, v126, v127
	v_max3_f32 v99, v99, v128, v129
	s_waitcnt lgkmcnt(6)
	v_mfma_scale_f32_32x32x64_f8f6f4 v[66:81], v[90:97], v[154:161], v[66:81], v220, v220 op_sel_hi:[0,0,0]
	v_max3_f32 v99, v99, v130, v131
	v_max3_f32 v99, v99, v132, v133
	v_max3_f32 v99, v99, v134, v135
	v_max3_f32 v99, v99, v136, v137
	v_max3_f32 v99, v99, v138, v139
	v_max3_f32 v99, v99, v140, v141
	v_max3_f32 v99, v99, v142, v143
	v_max3_f32 v99, v99, v144, v145
	v_mov_b32_e32 v100, v99
	v_mov_b32_e32 v186, 1.0
	s_nop 0
	v_permlane32_swap_b32_e32 v99, v100
	v_max_f32_e32 v99, v99, v100
	v_cmp_ge_f32_e32 vcc, s88, v99
	s_cmp_eq_u64 vcc, exec
	s_cbranch_scc1 .LBB0_1735
	v_add_f32_e32 v99, -4.0, v99
	v_max_f32_e32 v99, 0, v99
	v_exp_f32_e64 v186, -v99
	v_sub_f32_e32 v129, v129, v99
	v_sub_f32_e32 v128, v128, v99
	v_sub_f32_e32 v127, v127, v99
	v_sub_f32_e32 v126, v126, v99
	v_sub_f32_e32 v125, v125, v99
	v_sub_f32_e32 v124, v124, v99
	v_sub_f32_e32 v123, v123, v99
	v_sub_f32_e32 v122, v122, v99
	v_sub_f32_e32 v121, v121, v99
	v_sub_f32_e32 v120, v120, v99
	v_sub_f32_e32 v119, v119, v99
	v_sub_f32_e32 v118, v118, v99
	v_sub_f32_e32 v117, v117, v99
	v_sub_f32_e32 v116, v116, v99
	v_sub_f32_e32 v115, v115, v99
	v_sub_f32_e32 v114, v114, v99
	v_sub_f32_e32 v145, v145, v99
	v_sub_f32_e32 v144, v144, v99
	v_sub_f32_e32 v143, v143, v99
	v_sub_f32_e32 v142, v142, v99
	v_sub_f32_e32 v141, v141, v99
	v_sub_f32_e32 v140, v140, v99
	v_sub_f32_e32 v139, v139, v99
	v_sub_f32_e32 v138, v138, v99
	v_sub_f32_e32 v137, v137, v99
	v_sub_f32_e32 v136, v136, v99
	v_sub_f32_e32 v135, v135, v99
	v_sub_f32_e32 v134, v134, v99
	v_sub_f32_e32 v133, v133, v99
	v_sub_f32_e32 v132, v132, v99
	v_sub_f32_e32 v131, v131, v99
	v_sub_f32_e32 v130, v130, v99
	v_sub_f32_e32 v65, v65, v99
	v_sub_f32_e32 v64, v64, v99
	v_sub_f32_e32 v63, v63, v99
	v_sub_f32_e32 v62, v62, v99
	v_sub_f32_e32 v61, v61, v99
	v_sub_f32_e32 v60, v60, v99
	v_sub_f32_e32 v59, v59, v99
	v_sub_f32_e32 v58, v58, v99
	v_sub_f32_e32 v57, v57, v99
	v_sub_f32_e32 v56, v56, v99
	v_sub_f32_e32 v55, v55, v99
	v_sub_f32_e32 v54, v54, v99
	v_sub_f32_e32 v53, v53, v99
	v_sub_f32_e32 v52, v52, v99
	v_sub_f32_e32 v51, v51, v99
	v_sub_f32_e32 v50, v50, v99

.LBB0_1737:
	s_barrier
	global_load_dwordx4 v[204:207], v192, s[98:99] offset:192
	global_load_dwordx4 v[208:211], v189, s[98:99]
	global_load_dwordx2 v[196:197], v214, s[98:99] offset:2048
	ds_read_b128 v[86:89], v223 offset:49168
	ds_read_b128 v[82:85], v223 offset:49152
	ds_read_b128 v[98:101], v223 offset:53760
	ds_read_b128 v[102:105], v223 offset:53776
	ds_read_b128 v[156:159], v223 offset:49232
	ds_read_b128 v[240:243], v223 offset:49216
	s_waitcnt lgkmcnt(4)
	v_add_f32_e32 v160, v118, v114
	v_mfma_scale_f32_32x32x64_f8f6f4 v[82:97], v[82:87], v[174:179], v[50:65], v88, v198 op_sel_hi:[0,0,0] cbsz:2 blgp:2
	v_cvt_pk_fp8_f32 v154, v114, v115
	v_cvt_pk_fp8_f32 v155, v130, v131
	v_cvt_pk_fp8_f32 v154, v116, v117 op_sel:[0,0,1]
	v_cvt_pk_fp8_f32 v155, v132, v133 op_sel:[0,0,1]
	v_add_f32_e32 v114, v119, v115
	v_add_f32_e32 v115, v120, v116
	v_permlane32_swap_b32_e32 v154, v155
	ds_read_b128 v[246:249], v223 offset:53824
	ds_read_b128 v[250:253], v223 offset:53840
	v_add_f32_e32 v116, v121, v117
	s_waitcnt lgkmcnt(3)
	v_mfma_scale_f32_32x32x64_f8f6f4 v[98:113], v[98:103], v[174:179], v[50:65], v104, v198 op_sel_hi:[0,0,0] cbsz:2 blgp:2
	v_add_f32_e32 v117, v122, v160
	v_add_f32_e32 v114, v123, v114
	v_mov_b32_e32 v244, v156
	v_mov_b32_e32 v245, v157
	v_add_f32_e32 v115, v124, v115
	v_add_f32_e32 v116, v125, v116
	v_add_f32_e32 v159, v126, v117
	v_add_f32_e32 v160, v127, v114
	v_add_f32_e32 v161, v128, v115
	v_add_f32_e32 v200, v129, v116
	ds_read_b128 v[232:235], v222
	ds_read_b128 v[236:239], v222 offset:16
	s_waitcnt lgkmcnt(4)
	v_mfma_scale_f32_32x32x64_f8f6f4 v[82:97], v[240:245], v[180:185], v[82:97], v158, v202 op_sel_hi:[0,0,0] cbsz:2 blgp:2
	v_cvt_pk_fp8_f32 v156, v118, v119
	v_cvt_pk_fp8_f32 v157, v134, v135
	v_cvt_pk_fp8_f32 v156, v120, v121 op_sel:[0,0,1]
	v_cvt_pk_fp8_f32 v157, v136, v137 op_sel:[0,0,1]
	v_add_f32_e32 v130, v130, v159
	v_add_f32_e32 v131, v131, v160
	v_permlane32_swap_b32_e32 v156, v157
	s_waitcnt lgkmcnt(2)
	v_add_f32_e32 v132, v132, v161
	v_add_f32_e32 v133, v133, v200
	v_add_f32_e32 v130, v134, v130
	ds_read_b128 v[114:117], v222 offset:2560
	ds_read_b128 v[118:121], v222 offset:2576
	v_mfma_scale_f32_32x32x64_f8f6f4 v[98:113], v[246:251], v[180:185], v[98:113], v252, v202 op_sel_hi:[0,0,0] cbsz:2 blgp:2
	v_cvt_pk_fp8_f32 v158, v122, v123
	v_cvt_pk_fp8_f32 v159, v138, v139
	v_cvt_pk_fp8_f32 v158, v124, v125 op_sel:[0,0,1]
	v_cvt_pk_fp8_f32 v159, v140, v141 op_sel:[0,0,1]
	v_add_f32_e32 v122, v135, v131
	v_add_f32_e32 v123, v136, v132
	v_permlane32_swap_b32_e32 v158, v159
	v_add_f32_e32 v124, v137, v133
	s_waitcnt lgkmcnt(2)
	v_mfma_scale_f32_32x32x64_f8f6f4 v[82:97], v[232:239], v[146:153], v[82:97], v220, v1 op_sel_hi:[0,0,0]
	v_add_f32_e32 v125, v138, v130
	v_add_f32_e32 v122, v139, v122
	v_add_f32_e32 v123, v140, v123
	v_add_f32_e32 v124, v141, v124
	v_add_f32_e32 v125, v142, v125
	v_add_f32_e32 v122, v143, v122
	v_add_f32_e32 v123, v144, v123
	v_add_f32_e32 v124, v145, v124
	v_cvt_pk_fp8_f32 v160, v126, v127
	v_cvt_pk_fp8_f32 v161, v142, v143
	v_cvt_pk_fp8_f32 v160, v128, v129 op_sel:[0,0,1]
	v_cvt_pk_fp8_f32 v161, v144, v145 op_sel:[0,0,1]
	s_waitcnt lgkmcnt(0)
	v_mfma_scale_f32_32x32x64_f8f6f4 v[98:113], v[114:121], v[146:153], v[98:113], v220, v1 op_sel_hi:[0,0,0]
	v_add_f32_e32 v114, v125, v122
	v_add_f32_e32 v115, v123, v124
	v_permlane32_swap_b32_e32 v160, v161
	v_add_f32_e32 v130, v114, v115
	v_mov_b32_e32 v131, v130
	v_add_u32_e32 v114, s4, v224
	s_waitcnt vmcnt(0)
	ds_write_b128 v114, v[204:207]
	ds_write_b128 v203, v[208:211]
	ds_write_b64 v227, v[196:197]
	v_add_u32_e32 v132, s10, v191
	ds_read_b128 v[122:125], v132
	ds_read_b128 v[126:129], v132 offset:16
	v_max3_f32 v114, v82, s87, v83
	v_max3_f32 v114, v114, v84, v85
	v_max3_f32 v114, v114, v86, v87
	v_permlane32_swap_b32_e32 v130, v131
	v_max3_f32 v133, v114, v88, v89
	ds_read_b128 v[114:117], v132 offset:2560
	ds_read_b128 v[118:121], v132 offset:2576
	ds_read_b128 v[232:235], v132 offset:5120
	ds_read_b128 v[236:239], v132 offset:5136
	ds_read_b128 v[240:243], v132 offset:7680
	ds_read_b128 v[244:247], v132 offset:7696
	v_max3_f32 v133, v133, v90, v91
	v_max3_f32 v133, v133, v92, v93
	v_max3_f32 v133, v133, v94, v95
	v_max3_f32 v133, v133, v96, v97
	s_waitcnt lgkmcnt(6)
	v_mfma_scale_f32_32x32x64_f8f6f4 v[66:81], v[122:129], v[154:161], v[66:81], v220, v220 op_sel_hi:[0,0,0]
	v_max3_f32 v133, v133, v98, v99
	v_max3_f32 v133, v133, v100, v101
	v_max3_f32 v133, v133, v102, v103
	v_max3_f32 v133, v133, v104, v105
	v_max3_f32 v133, v133, v106, v107
	v_max3_f32 v133, v133, v108, v109
	v_max3_f32 v133, v133, v110, v111
	v_max3_f32 v133, v133, v112, v113
	v_mov_b32_e32 v134, v133
	v_mov_b32_e32 v138, 1.0
	s_nop 0
	v_permlane32_swap_b32_e32 v133, v134
	v_max_f32_e32 v133, v133, v134
	v_cmp_ge_f32_e32 vcc, s88, v133
	s_cmp_eq_u64 vcc, exec
	s_cbranch_scc1 .LBB0_1739
	v_add_f32_e32 v133, -4.0, v133
	v_max_f32_e32 v133, 0, v133
	v_exp_f32_e64 v138, -v133
	v_sub_f32_e32 v97, v97, v133
	v_sub_f32_e32 v96, v96, v133
	v_sub_f32_e32 v95, v95, v133
	v_sub_f32_e32 v94, v94, v133
	v_sub_f32_e32 v93, v93, v133
	v_sub_f32_e32 v92, v92, v133
	v_sub_f32_e32 v91, v91, v133
	v_sub_f32_e32 v90, v90, v133
	v_sub_f32_e32 v89, v89, v133
	v_sub_f32_e32 v88, v88, v133
	v_sub_f32_e32 v87, v87, v133
	v_sub_f32_e32 v86, v86, v133
	v_sub_f32_e32 v85, v85, v133
	v_sub_f32_e32 v84, v84, v133
	v_sub_f32_e32 v83, v83, v133
	v_sub_f32_e32 v82, v82, v133
	v_sub_f32_e32 v113, v113, v133
	v_sub_f32_e32 v112, v112, v133
	v_sub_f32_e32 v111, v111, v133
	v_sub_f32_e32 v110, v110, v133
	v_sub_f32_e32 v109, v109, v133
	v_sub_f32_e32 v108, v108, v133
	v_sub_f32_e32 v107, v107, v133
	v_sub_f32_e32 v106, v106, v133
	v_sub_f32_e32 v105, v105, v133
	v_sub_f32_e32 v104, v104, v133
	v_sub_f32_e32 v103, v103, v133
	v_sub_f32_e32 v102, v102, v133
	v_sub_f32_e32 v101, v101, v133
	v_sub_f32_e32 v100, v100, v133
	v_sub_f32_e32 v99, v99, v133
	v_sub_f32_e32 v98, v98, v133
	v_sub_f32_e32 v65, v65, v133
	v_sub_f32_e32 v64, v64, v133
	v_sub_f32_e32 v63, v63, v133
	v_sub_f32_e32 v62, v62, v133
	v_sub_f32_e32 v61, v61, v133
	v_sub_f32_e32 v60, v60, v133
	v_sub_f32_e32 v59, v59, v133
	v_sub_f32_e32 v58, v58, v133
	v_sub_f32_e32 v57, v57, v133
	v_sub_f32_e32 v56, v56, v133
	v_sub_f32_e32 v55, v55, v133
	v_sub_f32_e32 v54, v54, v133
	v_sub_f32_e32 v53, v53, v133
	v_sub_f32_e32 v52, v52, v133
	v_sub_f32_e32 v51, v51, v133
	v_sub_f32_e32 v50, v50, v133
